# attention: reads-before-loads ordering applied to waves 4-7 as well
# baseline (speedup 1.0000x reference)
; #define LAS __attribute__((address_space(3)))
; __device__ __forceinline__ float shx32(float v, int lane) { return __int_as_float(__builtin_amdgcn_ds_bpermute((lane ^ 32) << 2, __float_as_int(v))); }
; __device__ __forceinline__ float fexp2(float x) { return __builtin_amdgcn_exp2f(x); }
; __device__ __forceinline__ float max3f(float a, float b, float c) { float d; asm("v_max3_f32 %0, %1, %2, %3" : "=v"(d) : "v"(a), "v"(b), "v"(c)); return d; }
; #define ATT_LOADK(rk, rr, kt_) do { if (MODE == 3 && (kt_) > 1) break; rk = *(const u32x4*)(gkn + (size_t)(kt_) * 64 * 512); rr = *(const u32x4*)(gkr + (size_t)(kt_) * 64 * 32); } while (0)
; template <int MODE>
; __device__ __forceinline__ void attn_pv(const LAS unsigned char* vb_, f32x16 (&st)[2], f32x16 (&ot)[2], float& mrun, float& lsum, const int ql, const int hf, const int lane) {
;     if (MODE != 1) {
;     float mx = max3f(st[0][0], st[1][0], st[0][1]), my = max3f(st[1][1], st[0][2], st[1][2]);
; #pragma unroll
;     for (int i = 3; i < 15; i += 2) { mx = max3f(mx, st[0][i], st[1][i]); my = max3f(my, st[0][i + 1], st[1][i + 1]); }
;     mx = max3f(mx, st[0][15], st[1][15]); mx = max3f(mx, my, my);
;     if (__builtin_amdgcn_ballot_w64(mx > mrun + 8.0f) != 0ull) {
;         mx = fmaxf(mx, shx32(mx, lane));
;         const float mnew = (mx > mrun + 8.0f) ? mx : mrun;
;         const float alpha = fexp2(mrun - mnew);
;         mrun = mnew; lsum *= alpha;
; #pragma unroll
;         for (int i = 0; i < 16; ++i) { ot[0][i] *= alpha; ot[1][i] *= alpha; }
;     }
;     float ps = 0.f;
; #pragma unroll
;     for (int kb = 0; kb < 2; ++kb)
; #pragma unroll
;         for (int i = 0; i < 16; ++i) { const float p = fexp2(st[kb][i] - mrun); st[kb][i] = p; ps += p; }
;     lsum += ps;
;     } else lsum += st[0][0];
; #pragma unroll
;     for (int kb = 0; kb < 2; ++kb)
; #pragma unroll
; template <int MODE>
; __device__ __forceinline__ void attn_phase(const Args& a, bool do_ctx, LAS unsigned char* lds, const int wid_s) {
;     ...
;         for (int t = 0; t < nkt; t += 2) {
;             if (t + 2 < nkt) ATT_LOADK(kK, kR, t + 2);
;             ATT_LOADV(vV, t + 1);
;             attn_qk<MODE>(lds + KBUF, qf, sb, ql, hf);
;             __builtin_amdgcn_sched_barrier(0);
;             attn_pv<MODE>(ldsv, sa, ot, mrun, lsum, ql, hf, lane);
;             if (t + 2 < nkt) ATT_WRITEK(kK, kR, 0);
.LattB_e:
	ds_read_b128 v[64:67], v165 offset:13312
	ds_read_b128 v[168:171], v165 offset:13344
	ds_read_b128 v[68:71], v165 offset:19968
	ds_read_b128 v[172:175], v165 offset:20000
	ds_read_b128 v[176:179], v165 offset:13376
	ds_read_b128 v[180:183], v165 offset:13408
	ds_read_b128 v[184:187], v165 offset:20032
	ds_read_b128 v[188:191], v165 offset:20064
	ds_read_b128 v[206:209], v240 offset:31232
	ds_read_b128 v[210:213], v240 offset:26624
	ds_read_b128 v[214:217], v240 offset:31264
	ds_read_b128 v[218:221], v240 offset:26656
	ds_read_b128 v[222:225], v240 offset:31296
	ds_read_b128 v[226:229], v240 offset:26688
	ds_read_b128 v[236:239], v240 offset:26720
	s_andn2_b64 vcc, exec, s[10:11]
	s_cbranch_vccnz .Latt_eB_noK
	global_load_dwordx4 v[120:123], v146, s[80:81]
	global_load_dwordx4 v[124:127], v148, s[82:83]
.Latt_eB_noK:
	global_load_dwordx4 v[128:131], v150, s[84:85] offset:128
	v_max3_f32 v156, v48, v32, v49
	v_max3_f32 v157, v33, v50, v34
	v_max3_f32 v156, v156, v51, v35
	v_max3_f32 v157, v157, v52, v36
	v_max3_f32 v156, v156, v53, v37
	v_max3_f32 v157, v157, v54, v38
	v_max3_f32 v156, v156, v55, v39
	v_max3_f32 v157, v157, v56, v40
	v_max3_f32 v156, v156, v57, v41
	v_max3_f32 v157, v157, v58, v42
	v_max3_f32 v156, v156, v59, v43
	v_max3_f32 v157, v157, v60, v44
	v_max3_f32 v156, v156, v61, v45
	v_max3_f32 v157, v157, v62, v46
	v_max3_f32 v156, v156, v63, v47
	v_max3_f32 v157, v156, v157, v157
	v_add_f32_e32 v156, 0x41000000, v143
	v_cmp_gt_f32_e32 vcc, v157, v156
	s_cbranch_vccnz .Latt_eB_nors_resc
.Latt_eB_nors:
	v_sub_f32_e32 v48, v48, v143
	v_sub_f32_e32 v49, v49, v143
	v_sub_f32_e32 v50, v50, v143
	v_sub_f32_e32 v51, v51, v143
	v_sub_f32_e32 v52, v52, v143
	v_sub_f32_e32 v53, v53, v143
	v_sub_f32_e32 v54, v54, v143
	v_sub_f32_e32 v55, v55, v143
	v_exp_f32_e32 v48, v48
	v_exp_f32_e32 v49, v49
	v_exp_f32_e32 v50, v50
	v_exp_f32_e32 v51, v51
	v_exp_f32_e32 v52, v52
	v_exp_f32_e32 v53, v53
	v_exp_f32_e32 v54, v54
	v_exp_f32_e32 v55, v55
	s_waitcnt lgkmcnt(11)
	v_mfma_f32_32x32x16_bf16 v[80:95], v[64:67], v[112:115], 0
	v_cvt_pk_bf16_f32 v152, v48, v49
	v_cvt_pk_bf16_f32 v153, v50, v51
	v_cvt_pk_bf16_f32 v154, v52, v53
	v_cvt_pk_bf16_f32 v155, v54, v55
	v_mfma_f32_32x32x16_bf16 v[64:79], v[68:71], v[112:115], 0
	v_pk_add_f32 v[230:231], v[48:49], v[50:51]
	v_pk_add_f32 v[230:231], v[230:231], v[52:53]
	v_pk_add_f32 v[230:231], v[230:231], v[54:55]
	v_mfma_f32_32x32x16_bf16 v[80:95], v[168:171], v[96:99], v[80:95]
	v_sub_f32_e32 v56, v56, v143
	v_sub_f32_e32 v57, v57, v143
	v_sub_f32_e32 v58, v58, v143
	v_sub_f32_e32 v59, v59, v143
	v_sub_f32_e32 v60, v60, v143
	v_sub_f32_e32 v61, v61, v143
	v_sub_f32_e32 v62, v62, v143
	v_sub_f32_e32 v63, v63, v143
	v_mfma_f32_32x32x16_bf16 v[64:79], v[172:175], v[96:99], v[64:79]
	ds_read_b128 v[168:171], v165 offset:13440
	ds_read_b128 v[172:175], v165 offset:13472
	ds_read_b128 v[192:195], v165 offset:20096
	ds_read_b128 v[196:199], v165 offset:20128
	v_exp_f32_e32 v56, v56
	v_exp_f32_e32 v57, v57
	v_exp_f32_e32 v58, v58
	v_exp_f32_e32 v59, v59
	s_waitcnt lgkmcnt(11)
	v_mfma_f32_32x32x16_bf16 v[80:95], v[176:179], v[100:103], v[80:95]
	ds_read_b128 a[0:3], v240 offset:31328
	v_exp_f32_e32 v60, v60
	v_exp_f32_e32 v61, v61
	v_exp_f32_e32 v62, v62
	v_exp_f32_e32 v63, v63
	v_mfma_f32_32x32x16_bf16 v[64:79], v[184:187], v[100:103], v[64:79]
	v_mfma_f32_32x32x16_bf16 v[80:95], v[180:183], v[104:107], v[80:95]
	v_cvt_pk_bf16_f32 v48, v56, v57
	v_cvt_pk_bf16_f32 v49, v58, v59
	v_cvt_pk_bf16_f32 v50, v60, v61
	v_cvt_pk_bf16_f32 v51, v62, v63
	v_mfma_f32_32x32x16_bf16 v[64:79], v[188:191], v[104:107], v[64:79]
	s_andn2_b64 vcc, exec, s[10:11]
	s_cbranch_vccnz .Latt_wskip_eB1
	s_waitcnt vmcnt(2)
	ds_write_b128 v162, v[120:123]
	s_and_saveexec_b64 s[2:3], s[6:7]
	s_cbranch_execz .Latt_wk_eB1
	s_waitcnt vmcnt(1)
	ds_write_b128 v164, v[124:127] offset:128

; #define LAS __attribute__((address_space(3)))
; __device__ __forceinline__ float shx32(float v, int lane) { return __int_as_float(__builtin_amdgcn_ds_bpermute((lane ^ 32) << 2, __float_as_int(v))); }
; __device__ __forceinline__ float fexp2(float x) { return __builtin_amdgcn_exp2f(x); }
; __device__ __forceinline__ float max3f(float a, float b, float c) { float d; asm("v_max3_f32 %0, %1, %2, %3" : "=v"(d) : "v"(a), "v"(b), "v"(c)); return d; }
; #define ATT_LOADK(rk, rr, kt_) do { if (MODE == 3 && (kt_) > 1) break; rk = *(const u32x4*)(gkn + (size_t)(kt_) * 64 * 512); rr = *(const u32x4*)(gkr + (size_t)(kt_) * 64 * 32); } while (0)
; template <int MODE>
; __device__ __forceinline__ void attn_pv(const LAS unsigned char* vb_, f32x16 (&st)[2], f32x16 (&ot)[2], float& mrun, float& lsum, const int ql, const int hf, const int lane) {
;     if (MODE != 1) {
;     float mx = max3f(st[0][0], st[1][0], st[0][1]), my = max3f(st[1][1], st[0][2], st[1][2]);
; #pragma unroll
;     for (int i = 3; i < 15; i += 2) { mx = max3f(mx, st[0][i], st[1][i]); my = max3f(my, st[0][i + 1], st[1][i + 1]); }
;     mx = max3f(mx, st[0][15], st[1][15]); mx = max3f(mx, my, my);
;     if (__builtin_amdgcn_ballot_w64(mx > mrun + 8.0f) != 0ull) {
;         mx = fmaxf(mx, shx32(mx, lane));
;         const float mnew = (mx > mrun + 8.0f) ? mx : mrun;
;         const float alpha = fexp2(mrun - mnew);
;         mrun = mnew; lsum *= alpha;
; #pragma unroll
;         for (int i = 0; i < 16; ++i) { ot[0][i] *= alpha; ot[1][i] *= alpha; }
;     }
;     float ps = 0.f;
; #pragma unroll
;     for (int kb = 0; kb < 2; ++kb)
; #pragma unroll
;         for (int i = 0; i < 16; ++i) { const float p = fexp2(st[kb][i] - mrun); st[kb][i] = p; ps += p; }
;     lsum += ps;
;     } else lsum += st[0][0];
; #pragma unroll
;     for (int kb = 0; kb < 2; ++kb)
; #pragma unroll
; template <int MODE>
; __device__ __forceinline__ void attn_phase(const Args& a, bool do_ctx, LAS unsigned char* lds, const int wid_s) {
;     ...
;             if (t + 3 < nkt) ATT_LOADK(kK, kR, t + 3);
;             if (t + 2 < nkt) ATT_LOADV(vV, t + 2);
;             if (t + 2 < nkt) attn_qk<MODE>(lds, qf, sa, ql, hf);
;             __builtin_amdgcn_sched_barrier(0);
;             attn_pv<MODE>(ldsv + VBUF, sb, ot, mrun, lsum, ql, hf, lane);
;             if (t + 3 < nkt) ATT_WRITEK(kK, kR, 1);
;             if (t + 2 < nkt) ATT_WRITEV(vV, 0);
.LattB_o:
	ds_read_b128 v[32:35], v165
	ds_read_b128 v[152:155], v165 offset:32
	ds_read_b128 v[36:39], v165 offset:6656
	ds_read_b128 v[206:209], v165 offset:6688
	ds_read_b128 v[210:213], v165 offset:64
	ds_read_b128 v[214:217], v165 offset:96
	ds_read_b128 v[218:221], v165 offset:6720
	ds_read_b128 v[222:225], v165 offset:6752
	ds_read_b128 v[176:179], v240 offset:35840
	ds_read_b128 v[180:183], v240 offset:40448
	ds_read_b128 v[184:187], v240 offset:35872
	ds_read_b128 v[188:191], v240 offset:40480
	ds_read_b128 v[192:195], v240 offset:35904
	ds_read_b128 v[196:199], v240 offset:40512
	ds_read_b128 v[172:175], v240 offset:35936
	s_andn2_b64 vcc, exec, s[10:11]
	s_cbranch_vccnz .Latt_oB_noK
	s_add_u32 s86, s80, 0x10000
	s_addc_u32 s87, s81, 0
	s_add_u32 s88, s82, 0x1000
	s_addc_u32 s89, s83, 0
	global_load_dwordx4 v[120:123], v146, s[86:87]
	global_load_dwordx4 v[124:127], v148, s[88:89]
.Latt_oB_noK:
	global_load_dwordx4 v[128:131], v150, s[84:85] offset:256
	v_max3_f32 v156, v80, v64, v81
	v_max3_f32 v157, v65, v82, v66
	v_max3_f32 v156, v156, v83, v67
	v_max3_f32 v157, v157, v84, v68
	v_max3_f32 v156, v156, v85, v69
	v_max3_f32 v157, v157, v86, v70
	v_max3_f32 v156, v156, v87, v71
	v_max3_f32 v157, v157, v88, v72
	v_max3_f32 v156, v156, v89, v73
	v_max3_f32 v157, v157, v90, v74
	v_max3_f32 v156, v156, v91, v75
	v_max3_f32 v157, v157, v92, v76
	v_max3_f32 v156, v156, v93, v77
	v_max3_f32 v157, v157, v94, v78
	v_max3_f32 v156, v156, v95, v79
	v_max3_f32 v157, v156, v157, v157
	v_add_f32_e32 v156, 0x41000000, v143
	v_cmp_gt_f32_e32 vcc, v157, v156
	s_cbranch_vccnz .Latt_oB_nors_resc
.Latt_oB_nors:
	v_sub_f32_e32 v80, v80, v143
	v_sub_f32_e32 v81, v81, v143
	v_sub_f32_e32 v82, v82, v143
	v_sub_f32_e32 v83, v83, v143
	v_sub_f32_e32 v84, v84, v143
	v_sub_f32_e32 v85, v85, v143
	v_sub_f32_e32 v86, v86, v143
	v_sub_f32_e32 v87, v87, v143
	v_exp_f32_e32 v80, v80
	v_exp_f32_e32 v81, v81
	v_exp_f32_e32 v82, v82
	v_exp_f32_e32 v83, v83
	v_exp_f32_e32 v84, v84
	v_exp_f32_e32 v85, v85
	v_exp_f32_e32 v86, v86
	v_exp_f32_e32 v87, v87
	s_waitcnt lgkmcnt(11)
	v_mfma_f32_32x32x16_bf16 v[48:63], v[32:35], v[112:115], 0
	v_cvt_pk_bf16_f32 v168, v80, v81
	v_cvt_pk_bf16_f32 v169, v82, v83
	v_cvt_pk_bf16_f32 v170, v84, v85
	v_cvt_pk_bf16_f32 v171, v86, v87
	v_mfma_f32_32x32x16_bf16 v[32:47], v[36:39], v[112:115], 0
	v_pk_add_f32 v[230:231], v[80:81], v[82:83]
	v_pk_add_f32 v[230:231], v[230:231], v[84:85]
	v_pk_add_f32 v[230:231], v[230:231], v[86:87]
	v_mfma_f32_32x32x16_bf16 v[48:63], v[152:155], v[96:99], v[48:63]
	v_sub_f32_e32 v88, v88, v143
	v_sub_f32_e32 v89, v89, v143
	v_sub_f32_e32 v90, v90, v143
	v_sub_f32_e32 v91, v91, v143
	v_sub_f32_e32 v92, v92, v143
	v_sub_f32_e32 v93, v93, v143
	v_sub_f32_e32 v94, v94, v143
	v_sub_f32_e32 v95, v95, v143
	v_mfma_f32_32x32x16_bf16 v[32:47], v[206:209], v[96:99], v[32:47]
	ds_read_b128 v[152:155], v165 offset:128
	ds_read_b128 v[206:209], v165 offset:160
	ds_read_b128 v[226:229], v165 offset:6784
	ds_read_b128 v[236:239], v165 offset:6816
	v_exp_f32_e32 v88, v88
	v_exp_f32_e32 v89, v89
	v_exp_f32_e32 v90, v90
	v_exp_f32_e32 v91, v91
	s_waitcnt lgkmcnt(11)
	v_mfma_f32_32x32x16_bf16 v[48:63], v[210:213], v[100:103], v[48:63]
	ds_read_b128 a[0:3], v240 offset:40544
	v_exp_f32_e32 v92, v92
	v_exp_f32_e32 v93, v93
	v_exp_f32_e32 v94, v94
	v_exp_f32_e32 v95, v95
	v_mfma_f32_32x32x16_bf16 v[32:47], v[218:221], v[100:103], v[32:47]
	v_mfma_f32_32x32x16_bf16 v[48:63], v[214:217], v[104:107], v[48:63]
	v_cvt_pk_bf16_f32 v80, v88, v89
	v_cvt_pk_bf16_f32 v81, v90, v91
	v_cvt_pk_bf16_f32 v82, v92, v93
	v_cvt_pk_bf16_f32 v83, v94, v95
	v_mfma_f32_32x32x16_bf16 v[32:47], v[222:225], v[104:107], v[32:47]
	s_andn2_b64 vcc, exec, s[10:11]
	s_cbranch_vccnz .Latt_wskip_oB1
	s_waitcnt vmcnt(1)
	ds_write_b128 v162, v[120:123] offset:13312
	s_and_saveexec_b64 s[2:3], s[6:7]
	s_cbranch_execz .Latt_wk_oB1
	s_waitcnt vmcnt(0)
	ds_write_b128 v164, v[124:127] offset:13440
